# v31 + static s_setprio 1 for waves 4-7 during the in-proj and up-GEMM epilogues (one wave per SIMD finishes and issues its stores while its partner still computes)
# baseline (speedup 1.0000x reference)
.LBB0_92:
	s_or_b64 exec, exec, s[0:1]
	v_lshl_add_u32 v182, s72, 7, v162
	v_ashrrev_i32_e32 v183, 31, v182
	v_readlane_b32 s0, v255, 49
	v_lshlrev_b64 v[78:79], 2, v[182:183]
	v_readlane_b32 s1, v255, 50
	s_waitcnt lgkmcnt(0)
	s_barrier
	v_cmp_lt_u32_e32 vcc, 0xff, v218
	s_nop 1
	s_cbranch_vccz .Lmy_epc_np
	s_setprio 1
.Lmy_epc_np:
	v_lshl_add_u64 v[82:83], s[16:17], 0, v[78:79]
	v_lshl_add_u64 v[84:85], s[0:1], 0, v[78:79]
	v_readlane_b32 s0, v255, 25
	v_readlane_b32 s1, v255, 26
	v_lshl_add_u64 v[102:103], s[18:19], 0, v[78:79]
	v_lshlrev_b32_e32 v209, 2, v162
	v_lshl_add_u64 v[86:87], s[0:1], 0, v[78:79]
	global_load_dwordx4 v[78:81], v[82:83], off offset:16
	global_load_dwordx4 v[90:93], v[82:83], off
	global_load_dwordx4 v[126:129], v[84:85], off offset:16
	global_load_dwordx4 v[114:117], v[84:85], off
	s_nop 0
	global_load_dwordx4 v[82:85], v[86:87], off offset:16
	global_load_dwordx4 v[98:101], v[86:87], off
	s_nop 0
	global_load_dwordx4 v[86:89], v[102:103], off offset:16
	s_nop 0
	global_load_dwordx4 v[102:105], v[102:103], off
	v_add_u32_e32 v170, s47, v209
	v_add_u32_e32 v162, s77, v209
	ds_read_b128 v[166:169], v162 offset:1024
	ds_read_b128 v[162:165], v162 offset:1040
	ds_read_b128 v[174:177], v170
	ds_read_b128 v[170:173], v170 offset:16
	s_mul_i32 s8, s43, 0xfe
	s_add_i32 s8, s8, -1
	v_add_u32_e32 v210, s8, v197
	v_mov_b32_e32 v184, v150
	v_mov_b32_e32 v185, v151
	v_mov_b32_e32 v188, v152
	v_mov_b32_e32 v189, v153
	v_mov_b32_e32 v194, v146
	v_mov_b32_e32 v195, v147
	v_mov_b32_e32 v186, v148
	v_mov_b32_e32 v187, v149
	v_cmp_gt_i32_e32 vcc, s76, v210
	v_mov_b32_dpp v184, v134 row_ror:15 row_mask:0xf bank_mask:0xf
	v_mov_b32_dpp v185, v135 row_ror:15 row_mask:0xf bank_mask:0xf
	v_mov_b32_dpp v188, v136 row_ror:15 row_mask:0xf bank_mask:0xf
	v_mov_b32_dpp v189, v137 row_ror:15 row_mask:0xf bank_mask:0xf
	v_mov_b32_dpp v194, v130 row_ror:15 row_mask:0xf bank_mask:0xf
	v_mov_b32_dpp v195, v131 row_ror:15 row_mask:0xf bank_mask:0xf
	v_mov_b32_dpp v186, v132 row_ror:15 row_mask:0xf bank_mask:0xf
	v_mov_b32_dpp v187, v133 row_ror:15 row_mask:0xf bank_mask:0xf
	s_waitcnt lgkmcnt(0)
	v_mov_b32_dpp v174, v150 row_shr:1 row_mask:0xf bank_mask:0xf
	v_mov_b32_dpp v184, v150 row_shl:1 row_mask:0xf bank_mask:0xf
	v_mov_b32_dpp v175, v151 row_shr:1 row_mask:0xf bank_mask:0xf
	v_mov_b32_dpp v185, v151 row_shl:1 row_mask:0xf bank_mask:0xf
	v_mov_b32_dpp v176, v152 row_shr:1 row_mask:0xf bank_mask:0xf
	v_mov_b32_dpp v188, v152 row_shl:1 row_mask:0xf bank_mask:0xf
	v_mov_b32_dpp v177, v153 row_shr:1 row_mask:0xf bank_mask:0xf
	v_mov_b32_dpp v189, v153 row_shl:1 row_mask:0xf bank_mask:0xf
	v_mov_b32_dpp v170, v146 row_shr:1 row_mask:0xf bank_mask:0xf
	v_mov_b32_dpp v194, v146 row_shl:1 row_mask:0xf bank_mask:0xf
	v_mov_b32_dpp v171, v147 row_shr:1 row_mask:0xf bank_mask:0xf
	v_mov_b32_dpp v195, v147 row_shl:1 row_mask:0xf bank_mask:0xf
	v_mov_b32_dpp v172, v148 row_shr:1 row_mask:0xf bank_mask:0xf
	v_mov_b32_dpp v186, v148 row_shl:1 row_mask:0xf bank_mask:0xf
	v_mov_b32_dpp v173, v149 row_shr:1 row_mask:0xf bank_mask:0xf
	v_mov_b32_dpp v187, v149 row_shl:1 row_mask:0xf bank_mask:0xf
	s_and_b64 s[10:11], s[52:53], vcc
	s_and_saveexec_b64 s[0:1], s[10:11]
	s_cbranch_execz .LBB0_94
	s_movk_i32 s2, 0x2000
	v_cmp_gt_i32_e32 vcc, s2, v210
	s_waitcnt vmcnt(0)
	v_pk_mul_f32 v[192:193], v[146:147], v[126:127]
	v_readlane_b32 s10, v253, 13
	v_cndmask_b32_e32 v191, v239, v220, vcc
	v_and_b32_e32 v211, v191, v210
	v_cmp_eq_u32_e32 vcc, 0, v211
	v_readlane_b32 s11, v253, 14
	s_nop 0
	v_cndmask_b32_e64 v190, 1.0, 0, vcc
	v_cmp_eq_u32_e32 vcc, v211, v191
	v_pk_mul_f32 v[214:215], v[190:191], v[78:79] op_sel_hi:[0,1]
	v_pk_fma_f32 v[170:171], v[214:215], v[170:171], v[192:193]
	v_cndmask_b32_e64 v212, 1.0, 0, vcc
	v_pk_mul_f32 v[192:193], v[212:213], v[82:83] op_sel_hi:[0,1]
	v_pk_fma_f32 v[170:171], v[192:193], v[194:195], v[170:171]
	v_pk_mul_f32 v[214:215], v[152:153], v[116:117]
	v_pk_add_f32 v[170:171], v[86:87], v[170:171]
	s_nop 0
	v_mul_f32_e32 v191, 0x3d372713, v170
	v_mul_f32_e32 v191, v170, v191
	v_mul_f32_e32 v192, 0x3d372713, v171
	v_fma_f32 v191, v170, v191, v170
	v_mul_f32_e32 v192, v171, v192
	v_mul_f32_e32 v191, 0x3f4c422a, v191
	v_fma_f32 v192, v171, v192, v171
	v_mul_f32_e32 v191, 0x4038aa3b, v191
	v_mul_f32_e32 v192, 0x3f4c422a, v192
	v_exp_f32_e32 v191, v191
	v_mul_f32_e32 v192, 0x4038aa3b, v192
	v_exp_f32_e32 v195, v192
	v_pk_mul_f32 v[192:193], v[148:149], v[128:129]
	v_add_f32_e32 v191, 1.0, v191
	v_rcp_f32_e32 v194, v191
	v_add_f32_e32 v191, 1.0, v195
	v_pk_mul_f32 v[216:217], v[190:191], v[92:93] op_sel_hi:[0,1]
	v_pk_fma_f32 v[176:177], v[216:217], v[176:177], v[214:215]
	v_pk_mul_f32 v[214:215], v[212:213], v[100:101] op_sel_hi:[0,1]
	v_pk_fma_f32 v[176:177], v[214:215], v[188:189], v[176:177]
	v_rcp_f32_e32 v195, v191
	v_pk_add_f32 v[176:177], v[104:105], v[176:177]
	s_nop 0
	v_mul_f32_e32 v188, 0x3d372713, v176
	v_mul_f32_e32 v188, v176, v188
	v_fma_f32 v188, v176, v188, v176
	v_mul_f32_e32 v188, 0x3f4c422a, v188
	v_mul_f32_e32 v188, 0x4038aa3b, v188
	v_exp_f32_e32 v191, v188
	v_mul_f32_e32 v188, 0x3d372713, v177
	v_mul_f32_e32 v188, v177, v188
	v_fma_f32 v188, v177, v188, v177
	v_mul_f32_e32 v188, 0x3f4c422a, v188
	v_mul_f32_e32 v188, 0x4038aa3b, v188
	v_exp_f32_e32 v211, v188
	v_add_f32_e32 v191, 1.0, v191
	v_pk_add_f32 v[188:189], v[194:195], 1.0 op_sel_hi:[1,0] neg_lo:[1,0] neg_hi:[1,0]
	v_rcp_f32_e32 v194, v191
	v_add_f32_e32 v191, 1.0, v211
	v_rcp_f32_e32 v195, v191
	v_pk_mul_f32 v[170:171], v[170:171], v[188:189]
	v_pk_add_f32 v[188:189], v[194:195], 1.0 op_sel_hi:[1,0] neg_lo:[1,0] neg_hi:[1,0]
	v_pk_mul_f32 v[158:159], v[158:159], v[170:171]
	v_pk_mul_f32 v[170:171], v[150:151], v[114:115]
	v_pk_mul_f32 v[176:177], v[176:177], v[188:189]
	v_pk_mul_f32 v[188:189], v[190:191], v[90:91] op_sel_hi:[0,1]
	v_pk_fma_f32 v[170:171], v[188:189], v[174:175], v[170:171]
	v_pk_mul_f32 v[174:175], v[212:213], v[98:99] op_sel_hi:[0,1]
	v_pk_fma_f32 v[170:171], v[174:175], v[184:185], v[170:171]
	v_pk_mul_f32 v[156:157], v[156:157], v[176:177]
	v_pk_mul_f32 v[176:177], v[190:191], v[80:81] op_sel_hi:[0,1]
	v_pk_add_f32 v[170:171], v[102:103], v[170:171]
	v_pk_fma_f32 v[172:173], v[176:177], v[172:173], v[192:193]
	v_pk_mul_f32 v[176:177], v[212:213], v[84:85] op_sel_hi:[0,1]
	v_mul_f32_e32 v174, 0x3d372713, v170
	v_mul_f32_e32 v175, 0x3d372713, v171
	v_pk_fma_f32 v[172:173], v[176:177], v[186:187], v[172:173]
	v_mul_f32_e32 v174, v170, v174
	v_mul_f32_e32 v175, v171, v175
	v_pk_add_f32 v[172:173], v[88:89], v[172:173]
	v_fma_f32 v174, v170, v174, v170
	v_fma_f32 v175, v171, v175, v171
	v_mul_f32_e32 v176, 0x3d372713, v172
	v_mul_f32_e32 v177, 0x3d372713, v173
	v_mul_f32_e32 v174, 0x3f4c422a, v174
	v_mul_f32_e32 v175, 0x3f4c422a, v175
	v_mul_f32_e32 v176, v172, v176
	v_mul_f32_e32 v177, v173, v177
	v_mul_f32_e32 v174, 0x4038aa3b, v174
	v_mul_f32_e32 v175, 0x4038aa3b, v175
	v_fma_f32 v176, v172, v176, v172
	v_fma_f32 v177, v173, v177, v173
	v_exp_f32_e32 v174, v174
	v_exp_f32_e32 v175, v175
	v_mul_f32_e32 v176, 0x3f4c422a, v176
	v_mul_f32_e32 v177, 0x3f4c422a, v177
	v_mul_f32_e32 v176, 0x4038aa3b, v176
	v_mul_f32_e32 v177, 0x4038aa3b, v177
	v_exp_f32_e32 v176, v176
	v_exp_f32_e32 v177, v177
	v_add_f32_e32 v174, 1.0, v174
	v_add_f32_e32 v175, 1.0, v175
	v_rcp_f32_e32 v174, v174
	v_rcp_f32_e32 v175, v175
	v_add_f32_e32 v176, 1.0, v176
	v_add_f32_e32 v177, 1.0, v177
	v_rcp_f32_e32 v176, v176
	v_rcp_f32_e32 v177, v177
	v_pk_add_f32 v[174:175], v[174:175], 1.0 op_sel_hi:[1,0] neg_lo:[1,0] neg_hi:[1,0]
	s_nop 0
	v_pk_mul_f32 v[170:171], v[170:171], v[174:175]
	s_nop 0
	v_pk_mul_f32 v[154:155], v[154:155], v[170:171]
	v_pk_add_f32 v[170:171], v[176:177], 1.0 op_sel_hi:[1,0] neg_lo:[1,0] neg_hi:[1,0]
	v_cvt_pk_bf16_f32 v154, v154, v155
	v_pk_mul_f32 v[170:171], v[172:173], v[170:171]
	v_cvt_pk_bf16_f32 v155, v156, v157
	v_cvt_pk_bf16_f32 v156, v158, v159
	v_mov_b64_e32 v[158:159], s[10:11]
	v_pk_mul_f32 v[160:161], v[160:161], v[170:171]
	v_mad_i64_i32 v[158:159], s[10:11], v210, s61, v[158:159]
	v_cvt_pk_bf16_f32 v157, v160, v161
	v_lshl_add_u64 v[158:159], v[182:183], 1, v[158:159]
	global_store_dwordx4 v[158:159], v[154:157], off

.LBB0_108:
	s_or_b64 exec, exec, s[0:1]
	s_setprio 0
	v_readlane_b32 s0, v255, 45
	v_readlane_b32 s1, v255, 46
	s_and_b64 vcc, exec, s[0:1]
	s_mov_b64 s[0:1], -1
	s_cbranch_vccnz .LBB0_69
	v_readlane_b32 s0, v255, 27
	v_readlane_b32 s1, v255, 28
	s_andn2_b64 vcc, exec, s[0:1]
	s_cbranch_vccnz .LBB0_68
	s_barrier
	s_branch .LBB0_68

.LBB0_805:
	v_cmp_lt_u32_e32 vcc, 0xff, v218
	s_nop 1
	s_cbranch_vccz .Lmy_epg_np
	s_setprio 1

.LBB0_807:
	s_setprio 0
	s_andn2_b64 vcc, exec, s[38:39]
	s_mov_b64 s[8:9], -1
	s_cbranch_vccnz .LBB0_793
	s_branch .LBB0_810

.LBB0_812:
	s_setprio 0
	s_waitcnt vmcnt(0)
	v_readlane_b32 s52, v255, 10
	v_readlane_b32 s50, v255, 15
	v_readlane_b32 s53, v255, 11
	v_readlane_b32 s51, v255, 16
	s_movk_i32 s47, 0x3ff
	v_readlane_b32 s54, v255, 17
	v_readlane_b32 s55, v255, 18
	s_mov_b32 s48, 0xc000
	s_movk_i32 s49, 0x1fff
	s_movk_i32 s42, 0xdff
	s_movk_i32 s43, 0x1dff
	s_barrier
